# stage-B schedule C with a 40 / 24 K-tile split
# speedup vs baseline: 1.0073x; 1.0073x over previous
.Lp9_stage_b:
	s_mov_b32 s100, 10
	s_movk_i32 s91, 36
	s_movk_i32 s97, 37
	s_cmpk_lt_u32 s101, 0x80
	s_cbranch_scc0 .Lp9_hi
	s_mov_b32 s96, 1
	s_add_u32 s4, s78, 0x8000000
	s_addc_u32 s5, s79, 0
	s_add_i32 s98, s101, 0x200
	s_movk_i32 s99, 0x280
	s_branch .Lp9_body

.Lp9_to_seam9:
	s_cmp_eq_u32 s96, 2
	s_cbranch_scc0 .Lp9_ts9
	s_mov_b32 s96, 4
	s_movk_i32 s91, 20
	s_movk_i32 s97, 21
	s_add_u32 s4, s78, 0x8001400
	s_addc_u32 s5, s79, 0
	s_add_u32 s74, s74, 0x1400
	s_addc_u32 s75, s75, 0
	s_add_i32 s98, s101, 0x180
	s_movk_i32 s99, 0x280
	v_readlane_b32 s12, v255, 20
	v_readlane_b32 s13, v255, 21
	v_readlane_b32 s14, v255, 22
	v_readlane_b32 s15, v255, 23
	v_readlane_b32 s16, v255, 24
	v_readlane_b32 s17, v255, 25
	v_readlane_b32 s18, v255, 26
	v_readlane_b32 s19, v255, 27
	v_readlane_b32 s20, v255, 28
	v_readlane_b32 s21, v255, 29
	v_readlane_b32 s22, v255, 30
	v_readlane_b32 s23, v255, 31
	v_readlane_b32 s24, v255, 32
	v_readlane_b32 s25, v255, 33
	v_readlane_b32 s26, v255, 34
	v_readlane_b32 s27, v255, 35
	v_readlane_b32 s28, v255, 36
	v_readlane_b32 s29, v255, 37
	v_readlane_b32 s30, v255, 38
	v_readlane_b32 s31, v255, 39
	s_waitcnt vmcnt(0)
	s_nop 3
	s_branch .Lp9_body
